# attention: K/V LDS read bases use per-unit precomputed lane sums (2 VALU fewer per wave-tile)
# speedup vs baseline: 1.0022x; 1.0022x over previous
; #define GAS __attribute__((address_space(1)))
; __device__ __forceinline__ unsigned pk2(float lo, float hi) { return cvtpk(lo, hi); }
; __device__ __forceinline__ float bflo(unsigned w) { return __uint_as_float(w << 16); }
; __device__ __forceinline__ float bfhi(unsigned w) { return __uint_as_float(w & 0xffff0000u); }
; __device__ __forceinline__ void attn_unit(LAS unsigned char* lds, const GAS bf16_t* __restrict__ QR, const GAS float* __restrict__ ssq, const GAS float* __restrict__ RT, const GAS bf16_t* __restrict__ K, const GAS bf16_t* __restrict__ Vt, GAS bf16_t* __restrict__ A2, int b, int h, int qb, int tid, i ...
;     const int r32 = lane & 31, hi = lane >> 5, q0 = qb * 512 + wave * 64, r32s = (r32 & ~12) | ((r32 & 4) << 1) | ((r32 & 8) >> 1);
;     bf16x8 qa[6], qc[6];
; #pragma unroll
;     for (int sub = 0; sub < 2; ++sub) {
;         const int s = q0 + 32 * sub + r32, row = b * SEQ + s;
;         const GAS bf16_t* Qp = QR + (size_t)row * 768 + h * 96 + 8 * hi;
;         const float sc = rsqrtf(ssq[row] * (1.f / 256.f) + EPS) * QSCALE;
; #pragma unroll
;         for (int d0 = 0; d0 < 6; ++d0) {
;             const u32x4 raw = *(const GAS u32x4*)(Qp + 16 * d0);
;             float v[8];
; #pragma unroll
;             for (int j = 0; j < 4; ++j) { v[2 * j] = bflo(raw[j]) * sc; v[2 * j + 1] = bfhi(raw[j]) * sc; }
;             if (d0 >= 4) { const GAS float* rt = RT + (d0 == 4 ? (s >> 6) : (s & 63)) * 16;
; #pragma unroll
;                 for (int j = 0; j < 8; ++j) { const float pt = __shfl_xor(v[j], 32), cs = rt[2 * j], sn = rt[2 * j + 1]; v[j] = hi ? v[j] * cs + pt * sn : v[j] * cs - pt * sn; } }
;             u32x4 w; w.x = pk2(v[0], v[1]); w.y = pk2(v[2], v[3]); w.z = pk2(v[4], v[5]); w.w = pk2(v[6], v[7]);
;             if (sub == 0) qa[d0] = __builtin_bit_cast(bf16x8, w); else qc[d0] = __builtin_bit_cast(bf16x8, w);
;         }
;     }
.LBB0_133:
	s_lshl_b32 s22, s17, 9
	s_and_b32 s43, s22, 0x1e00
	s_ashr_i32 s1, s17, 7
	s_add_i32 s43, s43, s65
	s_bfe_u32 s42, s17, 0x30004
	v_or_b32_e32 v1, s43, v151
	s_lshl_b32 s64, s1, 13
	s_mul_i32 s50, s42, 0xc0
	v_add_u32_e32 v2, s64, v1
	v_lshl_add_u64 v[6:7], v[156:157], 0, s[50:51]
	s_movk_i32 s22, 0x600
	v_ashrrev_i32_e32 v3, 31, v2
	v_mad_i64_i32 v[8:9], s[24:25], v2, s22, v[6:7]
	v_lshl_add_u64 v[2:3], v[2:3], 2, s[78:79]
	global_load_dwordx4 v[10:13], v[8:9], off
	global_load_dwordx4 v[18:21], v[8:9], off offset:32
	global_load_dwordx4 v[34:37], v[8:9], off offset:64
	global_load_dwordx4 v[38:41], v[8:9], off offset:96
	global_load_dword v64, v[2:3], off
	v_or_b32_e32 v1, 32, v1
	v_add_u32_e32 v30, s64, v1
	v_ashrrev_i32_e32 v31, 31, v30
	v_mad_i64_i32 v[32:33], s[24:25], v30, s22, v[6:7]
	v_lshl_add_u64 v[30:31], v[30:31], 2, s[78:79]
	global_load_dwordx4 v[14:17], v[158:159], off offset:48
	global_load_dwordx4 v[22:25], v[158:159], off offset:32
	global_load_dwordx4 v[26:29], v[158:159], off offset:16
	global_load_dwordx4 v[42:45], v[158:159], off
	global_load_dwordx4 v[2:5], v[8:9], off offset:128
	global_load_dwordx4 v[46:49], v[8:9], off offset:160
	s_nop 0
	global_load_dwordx4 v[6:9], v[32:33], off
	s_nop 0
	global_load_dword v31, v[30:31], off
	s_ashr_i32 s24, s43, 2
	s_ashr_i32 s25, s24, 31
	s_lshl_b64 s[24:25], s[24:25], 2
	s_add_u32 s56, s34, s24
	s_addc_u32 s57, s35, s25
	v_lshlrev_b32_e32 v1, 6, v1
	v_and_b32_e32 v1, 0xfc0, v1
	s_lshl_b32 s1, s1, 3
	s_or_b32 s1, s1, s42
	s_mul_i32 s23, s1, 0x18c000
	s_mul_hi_i32 s22, s1, 0x18c000
	s_add_u32 s24, s84, s23
	s_addc_u32 s25, s85, s22
	s_mul_hi_i32 s22, s1, 0x108000
	s_mul_i32 s1, s1, 0x108000
	s_add_u32 s26, s82, s1
	s_addc_u32 s27, s83, s22
	s_mov_b32 s50, 2
	s_mov_b32 s49, 0
	v_mov_b32_e32 v179, 0xf149f2ca
	v_mov_b32_e32 v211, 0
	v_mov_b32_e32 v209, 0
	s_waitcnt vmcnt(12)
	v_lshlrev_b32_e32 v50, 16, v10
	v_and_b32_e32 v51, 0xffff0000, v10
	v_lshlrev_b32_e32 v10, 16, v11
	s_waitcnt vmcnt(9)
	v_and_b32_e32 v65, 0xffff0000, v40
	s_waitcnt vmcnt(8)
	v_fmamk_f32 v30, v64, 0x3b800000, v146
	v_mul_f32_e32 v64, 0x4b800000, v30
	v_cmp_gt_f32_e32 vcc, s14, v30
	v_and_b32_e32 v11, 0xffff0000, v11
	v_lshlrev_b32_e32 v54, 16, v18
	v_cndmask_b32_e32 v30, v30, v64, vcc
	v_rsq_f32_e32 v30, v30
	v_lshlrev_b32_e32 v64, 16, v40
	v_and_b32_e32 v55, 0xffff0000, v18
	v_lshlrev_b32_e32 v18, 16, v19
	v_mul_f32_e32 v40, 0x45800000, v30
	v_cndmask_b32_e32 v30, v30, v40, vcc
	v_mul_f32_e32 v30, 0x3e16c740, v30
	s_waitcnt vmcnt(0)
	v_pk_mul_f32 v[10:11], v[30:31], v[10:11] op_sel_hi:[0,1]
	v_cvt_pk_bf16_f32 v99, v10, v11
	v_lshlrev_b32_e32 v10, 16, v41
	v_and_b32_e32 v11, 0xffff0000, v41
	v_and_b32_e32 v19, 0xffff0000, v19
	v_pk_mul_f32 v[10:11], v[30:31], v[10:11] op_sel_hi:[0,1]
	v_lshlrev_b32_e32 v56, 16, v20
	v_and_b32_e32 v57, 0xffff0000, v20
	v_lshlrev_b32_e32 v20, 16, v21
	v_and_b32_e32 v21, 0xffff0000, v21
	v_pk_mul_f32 v[18:19], v[30:31], v[18:19] op_sel_hi:[0,1]
	v_cvt_pk_bf16_f32 v113, v10, v11
	v_lshlrev_b32_e32 v10, 16, v46
	v_and_b32_e32 v11, 0xffff0000, v46
	v_pk_mul_f32 v[20:21], v[30:31], v[20:21] op_sel_hi:[0,1]
	v_cvt_pk_bf16_f32 v103, v18, v19
	v_pk_mul_f32 v[18:19], v[30:31], v[10:11] op_sel_hi:[0,1]
	v_cvt_pk_bf16_f32 v105, v20, v21
	ds_bpermute_b32 v20, v153, v18
	ds_bpermute_b32 v21, v153, v19
	v_lshlrev_b32_e32 v58, 16, v34
	v_and_b32_e32 v59, 0xffff0000, v34
	v_lshlrev_b32_e32 v34, 16, v35
	v_and_b32_e32 v35, 0xffff0000, v35
	v_pk_mul_f32 v[34:35], v[30:31], v[34:35] op_sel_hi:[0,1]
	v_cvt_pk_bf16_f32 v107, v34, v35
	v_mov_b32_e32 v35, v44
	v_mov_b32_e32 v44, v43
	s_waitcnt lgkmcnt(0)
	v_pk_mul_f32 v[20:21], v[44:45], v[20:21]
	v_lshlrev_b32_e32 v60, 16, v36
	v_and_b32_e32 v61, 0xffff0000, v36
	v_lshlrev_b32_e32 v36, 16, v37
	v_and_b32_e32 v37, 0xffff0000, v37
	v_mov_b32_e32 v34, v42
	v_cndmask_b32_e64 v21, v21, -v21, s[6:7]
	v_cndmask_b32_e64 v20, v20, -v20, s[6:7]
	v_lshlrev_b32_e32 v52, 16, v12
	v_and_b32_e32 v53, 0xffff0000, v12
	v_lshlrev_b32_e32 v12, 16, v13
	v_and_b32_e32 v13, 0xffff0000, v13
	v_lshlrev_b32_e32 v62, 16, v38
	v_and_b32_e32 v63, 0xffff0000, v38
	v_lshlrev_b32_e32 v38, 16, v39
	v_and_b32_e32 v39, 0xffff0000, v39
	v_pk_mul_f32 v[36:37], v[30:31], v[36:37] op_sel_hi:[0,1]
	v_pk_fma_f32 v[34:35], v[18:19], v[34:35], v[20:21]
	v_lshlrev_b32_e32 v18, 16, v47
	v_and_b32_e32 v19, 0xffff0000, v47
	v_pk_mul_f32 v[12:13], v[30:31], v[12:13] op_sel_hi:[0,1]
	v_pk_mul_f32 v[38:39], v[30:31], v[38:39] op_sel_hi:[0,1]
	v_cvt_pk_bf16_f32 v109, v36, v37
	v_pk_mul_f32 v[36:37], v[30:31], v[18:19] op_sel_hi:[0,1]
	v_cvt_pk_bf16_f32 v101, v12, v13
	v_cvt_pk_bf16_f32 v111, v38, v39
	global_load_dwordx4 v[10:13], v[32:33], off offset:32
	global_load_dwordx4 v[18:21], v[32:33], off offset:64
	ds_bpermute_b32 v38, v153, v36
	ds_bpermute_b32 v39, v153, v37
	v_mov_b32_e32 v41, v28
	v_mov_b32_e32 v28, v27
	v_mov_b32_e32 v40, v26
	v_pk_mul_f32 v[50:51], v[30:31], v[50:51] op_sel_hi:[0,1]
	s_waitcnt lgkmcnt(0)
	v_pk_mul_f32 v[26:27], v[28:29], v[38:39]
	v_lshlrev_b32_e32 v28, 16, v48
	v_and_b32_e32 v29, 0xffff0000, v48
	v_pk_mul_f32 v[28:29], v[30:31], v[28:29] op_sel_hi:[0,1]
	v_cndmask_b32_e64 v27, v27, -v27, s[6:7]
	v_cndmask_b32_e64 v26, v26, -v26, s[6:7]
	ds_bpermute_b32 v38, v153, v28
	ds_bpermute_b32 v39, v153, v29
	v_pk_fma_f32 v[26:27], v[36:37], v[40:41], v[26:27]
	v_lshlrev_b32_e32 v40, 16, v49
	v_and_b32_e32 v41, 0xffff0000, v49
	v_pk_mul_f32 v[40:41], v[30:31], v[40:41] op_sel_hi:[0,1]
	ds_bpermute_b32 v42, v153, v40
	ds_bpermute_b32 v43, v153, v41
	v_mov_b32_e32 v37, v24
	v_mov_b32_e32 v24, v23
	v_mov_b32_e32 v36, v22
	s_waitcnt lgkmcnt(2)
; #define GAS __attribute__((address_space(1)))
; __device__ __forceinline__ unsigned pk2(float lo, float hi) { return cvtpk(lo, hi); }
; __device__ __forceinline__ float bflo(unsigned w) { return __uint_as_float(w << 16); }
; __device__ __forceinline__ float bfhi(unsigned w) { return __uint_as_float(w & 0xffff0000u); }
; __device__ __forceinline__ void attn_unit(LAS unsigned char* lds, const GAS bf16_t* __restrict__ QR, const GAS float* __restrict__ ssq, const GAS float* __restrict__ RT, const GAS bf16_t* __restrict__ K, const GAS bf16_t* __restrict__ Vt, GAS bf16_t* __restrict__ A2, int b, int h, int qb, int tid, i ...
;     ...
;     for (int sub = 0; sub < 2; ++sub) {
;         const int s = q0 + 32 * sub + r32, row = b * SEQ + s;
;         const GAS bf16_t* Qp = QR + (size_t)row * 768 + h * 96 + 8 * hi;
;         const float sc = rsqrtf(ssq[row] * (1.f / 256.f) + EPS) * QSCALE;
; #pragma unroll
;         for (int d0 = 0; d0 < 6; ++d0) {
;             const u32x4 raw = *(const GAS u32x4*)(Qp + 16 * d0);
;             float v[8];
; #pragma unroll
;             for (int j = 0; j < 4; ++j) { v[2 * j] = bflo(raw[j]) * sc; v[2 * j + 1] = bfhi(raw[j]) * sc; }
;             if (d0 >= 4) { const GAS float* rt = RT + (d0 == 4 ? (s >> 6) : (s & 63)) * 16;
; #pragma unroll
;                 for (int j = 0; j < 8; ++j) { const float pt = __shfl_xor(v[j], 32), cs = rt[2 * j], sn = rt[2 * j + 1]; v[j] = hi ? v[j] * cs + pt * sn : v[j] * cs - pt * sn; } }
;             u32x4 w; w.x = pk2(v[0], v[1]); w.y = pk2(v[2], v[3]); w.z = pk2(v[4], v[5]); w.w = pk2(v[6], v[7]);
;             if (sub == 0) qa[d0] = __builtin_bit_cast(bf16x8, w); else qc[d0] = __builtin_bit_cast(bf16x8, w);
;         }
	v_pk_mul_f32 v[22:23], v[24:25], v[38:39]
	v_pk_mul_f32 v[52:53], v[30:31], v[52:53] op_sel_hi:[0,1]
	v_cndmask_b32_e64 v39, v23, -v23, s[6:7]
	v_cndmask_b32_e64 v38, v22, -v22, s[6:7]
	global_load_dwordx4 v[22:25], v[32:33], off offset:96
	v_pk_fma_f32 v[38:39], v[28:29], v[36:37], v[38:39]
	v_mov_b32_e32 v29, v16
	v_mov_b32_e32 v16, v15
	v_mov_b32_e32 v28, v14
	s_waitcnt lgkmcnt(0)
	v_pk_mul_f32 v[14:15], v[16:17], v[42:43]
	v_pk_mul_f32 v[54:55], v[30:31], v[54:55] op_sel_hi:[0,1]
	v_pk_mul_f32 v[56:57], v[30:31], v[56:57] op_sel_hi:[0,1]
	v_pk_mul_f32 v[58:59], v[30:31], v[58:59] op_sel_hi:[0,1]
	v_pk_mul_f32 v[60:61], v[30:31], v[60:61] op_sel_hi:[0,1]
	v_pk_mul_f32 v[62:63], v[30:31], v[62:63] op_sel_hi:[0,1]
	v_pk_mul_f32 v[64:65], v[30:31], v[64:65] op_sel_hi:[0,1]
	v_cndmask_b32_e64 v15, v15, -v15, s[6:7]
	v_cndmask_b32_e64 v14, v14, -v14, s[6:7]
	v_fmamk_f32 v31, v31, 0x3b800000, v146
	v_pk_fma_f32 v[42:43], v[40:41], v[28:29], v[14:15]
	v_mul_f32_e32 v40, 0x4b800000, v31
	v_cmp_gt_f32_e32 vcc, s14, v31
	v_cvt_pk_bf16_f32 v114, v34, v35
	v_cvt_pk_bf16_f32 v115, v26, v27
	global_load_dwordx4 v[14:17], v[32:33], off offset:160
	global_load_dwordx4 v[26:29], v0, s[56:57] offset:16
	global_load_dwordx4 v[34:37], v0, s[56:57]
	v_cndmask_b32_e32 v31, v31, v40, vcc
	v_cvt_pk_bf16_f32 v116, v38, v39
	global_load_dwordx4 v[38:41], v[32:33], off offset:128
	v_rsq_f32_e32 v31, v31
	v_cvt_pk_bf16_f32 v117, v42, v43
	v_and_b32_e32 v33, 0xffff0000, v6
	v_lshlrev_b32_e32 v44, 16, v8
	v_mul_f32_e32 v32, 0x45800000, v31
	v_cndmask_b32_e32 v31, v31, v32, vcc
	v_mul_f32_e32 v42, 0x3e16c740, v31
	v_lshlrev_b32_e32 v32, 16, v6
	v_lshlrev_b32_e32 v6, 16, v7
	v_and_b32_e32 v7, 0xffff0000, v7
	v_pk_mul_f32 v[6:7], v[42:43], v[6:7] op_sel_hi:[0,1]
	v_and_b32_e32 v45, 0xffff0000, v8
	v_lshlrev_b32_e32 v8, 16, v9
	v_and_b32_e32 v9, 0xffff0000, v9
	v_cvt_pk_bf16_f32 v119, v6, v7
	v_pk_mul_f32 v[8:9], v[42:43], v[8:9] op_sel_hi:[0,1]
	v_pk_mul_f32 v[32:33], v[42:43], v[32:33] op_sel_hi:[0,1]
	v_cvt_pk_bf16_f32 v121, v8, v9
	v_cvt_pk_bf16_f32 v118, v32, v33
	v_pk_mul_f32 v[44:45], v[42:43], v[44:45] op_sel_hi:[0,1]
	v_cvt_pk_bf16_f32 v120, v44, v45
	v_cvt_pk_bf16_f32 v98, v50, v51
	v_cvt_pk_bf16_f32 v100, v52, v53
	v_cvt_pk_bf16_f32 v102, v54, v55
	v_cvt_pk_bf16_f32 v104, v56, v57
	v_cvt_pk_bf16_f32 v106, v58, v59
	s_waitcnt vmcnt(6)
	v_lshlrev_b32_e32 v6, 16, v10
	v_and_b32_e32 v7, 0xffff0000, v10
	v_pk_mul_f32 v[6:7], v[42:43], v[6:7] op_sel_hi:[0,1]
	v_lshlrev_b32_e32 v8, 16, v11
	v_and_b32_e32 v9, 0xffff0000, v11
	v_lshlrev_b32_e32 v10, 16, v12
	v_and_b32_e32 v11, 0xffff0000, v12
	v_lshlrev_b32_e32 v12, 16, v13
	v_and_b32_e32 v13, 0xffff0000, v13
	v_cvt_pk_bf16_f32 v122, v6, v7
	s_waitcnt vmcnt(5)
	v_lshlrev_b32_e32 v6, 16, v18
	v_and_b32_e32 v7, 0xffff0000, v18
	v_pk_mul_f32 v[8:9], v[42:43], v[8:9] op_sel_hi:[0,1]
	v_pk_mul_f32 v[10:11], v[42:43], v[10:11] op_sel_hi:[0,1]
	v_pk_mul_f32 v[12:13], v[42:43], v[12:13] op_sel_hi:[0,1]
	v_pk_mul_f32 v[32:33], v[42:43], v[6:7] op_sel_hi:[0,1]
	v_lshlrev_b32_e32 v6, 16, v19
	v_and_b32_e32 v7, 0xffff0000, v19
	v_cvt_pk_bf16_f32 v123, v8, v9
	v_cvt_pk_bf16_f32 v124, v10, v11
	v_cvt_pk_bf16_f32 v125, v12, v13
	v_pk_mul_f32 v[18:19], v[42:43], v[6:7] op_sel_hi:[0,1]
	global_load_dwordx4 v[6:9], v0, s[56:57] offset:48
	global_load_dwordx4 v[10:13], v0, s[56:57] offset:32
	v_lshlrev_b32_e32 v44, 16, v20
	v_and_b32_e32 v45, 0xffff0000, v20
	v_lshlrev_b32_e32 v20, 16, v21
	v_and_b32_e32 v21, 0xffff0000, v21
	v_cvt_pk_bf16_f32 v127, v18, v19
	v_pk_mul_f32 v[20:21], v[42:43], v[20:21] op_sel_hi:[0,1]
	s_waitcnt vmcnt(6)
	v_lshlrev_b32_e32 v18, 16, v22
	v_and_b32_e32 v19, 0xffff0000, v22
	v_pk_mul_f32 v[18:19], v[42:43], v[18:19] op_sel_hi:[0,1]
	v_cvt_pk_bf16_f32 v129, v20, v21
	v_lshlrev_b32_e32 v20, 16, v23
	v_and_b32_e32 v21, 0xffff0000, v23
	v_cvt_pk_bf16_f32 v130, v18, v19
	v_lshlrev_b32_e32 v18, 16, v2
	v_and_b32_e32 v19, 0xffff0000, v2
	v_pk_mul_f32 v[20:21], v[42:43], v[20:21] op_sel_hi:[0,1]
	v_lshlrev_b32_e32 v22, 16, v24
	v_and_b32_e32 v23, 0xffff0000, v24
	v_pk_mul_f32 v[18:19], v[30:31], v[18:19] op_sel_hi:[0,1]
	v_pk_mul_f32 v[22:23], v[42:43], v[22:23] op_sel_hi:[0,1]
	v_cvt_pk_bf16_f32 v131, v20, v21
	ds_bpermute_b32 v20, v153, v18
	ds_bpermute_b32 v21, v153, v19
	v_cvt_pk_bf16_f32 v132, v22, v23
	v_cvt_pk_bf16_f32 v126, v32, v33
	v_lshlrev_b32_e32 v24, 16, v25
	v_and_b32_e32 v25, 0xffff0000, v25
	s_waitcnt vmcnt(3)
	v_mov_b32_e32 v32, v34
	v_mov_b32_e32 v33, v36
	v_mov_b32_e32 v36, v35
	s_waitcnt vmcnt(2)
	v_lshlrev_b32_e32 v22, 16, v38
	v_and_b32_e32 v23, 0xffff0000, v38
	v_pk_mul_f32 v[34:35], v[42:43], v[22:23] op_sel_hi:[0,1]
	ds_bpermute_b32 v22, v153, v34
	ds_bpermute_b32 v23, v153, v35
	s_waitcnt lgkmcnt(2)
	v_pk_mul_f32 v[20:21], v[36:37], v[20:21]
	v_pk_mul_f32 v[24:25], v[42:43], v[24:25] op_sel_hi:[0,1]
	v_cndmask_b32_e64 v21, v21, -v21, s[6:7]
	v_cndmask_b32_e64 v20, v20, -v20, s[6:7]
	v_pk_fma_f32 v[18:19], v[18:19], v[32:33], v[20:21]
	v_cvt_pk_bf16_f32 v133, v24, v25
	v_cvt_pk_bf16_f32 v134, v18, v19
	s_waitcnt lgkmcnt(0)
	v_pk_mul_f32 v[36:37], v[36:37], v[22:23]
	global_load_dwordx4 v[18:21], v1, s[34:35] offset:16
	global_load_dwordx4 v[22:25], v1, s[34:35]
	v_lshlrev_b32_e32 v2, 16, v3
	v_and_b32_e32 v3, 0xffff0000, v3
	v_pk_mul_f32 v[44:45], v[42:43], v[44:45] op_sel_hi:[0,1]
	v_pk_mul_f32 v[2:3], v[30:31], v[2:3] op_sel_hi:[0,1]
	v_cvt_pk_bf16_f32 v128, v44, v45
	v_cndmask_b32_e64 v37, v37, -v37, s[6:7]
	v_cndmask_b32_e64 v36, v36, -v36, s[6:7]
	ds_bpermute_b32 v44, v153, v2
	ds_bpermute_b32 v45, v153, v3
	v_pk_fma_f32 v[36:37], v[32:33], v[34:35], v[36:37]
	v_lshlrev_b32_e32 v32, 16, v39
	v_and_b32_e32 v33, 0xffff0000, v39
	v_pk_mul_f32 v[38:39], v[42:43], v[32:33] op_sel_hi:[0,1]
	ds_bpermute_b32 v32, v153, v38
	ds_bpermute_b32 v33, v153, v39
	v_mov_b32_e32 v47, v28
	v_mov_b32_e32 v28, v27
	v_mov_b32_e32 v46, v26
	s_waitcnt lgkmcnt(2)
; #define GAS __attribute__((address_space(1)))
; __device__ __forceinline__ unsigned pk2(float lo, float hi) { return cvtpk(lo, hi); }
; __device__ __forceinline__ void attn_unit(LAS unsigned char* lds, const GAS bf16_t* __restrict__ QR, const GAS float* __restrict__ ssq, const GAS float* __restrict__ RT, const GAS bf16_t* __restrict__ K, const GAS bf16_t* __restrict__ Vt, GAS bf16_t* __restrict__ A2, int b, int h, int qb, int tid, i ...
;     ...
;             if (d0 >= 4) { const GAS float* rt = RT + (d0 == 4 ? (s >> 6) : (s & 63)) * 16;
; #pragma unroll
;                 for (int j = 0; j < 8; ++j) { const float pt = __shfl_xor(v[j], 32), cs = rt[2 * j], sn = rt[2 * j + 1]; v[j] = hi ? v[j] * cs + pt * sn : v[j] * cs - pt * sn; } }
;             u32x4 w; w.x = pk2(v[0], v[1]); w.y = pk2(v[2], v[3]); w.z = pk2(v[4], v[5]); w.w = pk2(v[6], v[7]);
;             if (sub == 0) qa[d0] = __builtin_bit_cast(bf16x8, w); else qc[d0] = __builtin_bit_cast(bf16x8, w);
;         }
;     }
;     const GAS unsigned char* Kg = (const GAS unsigned char*)(K + (size_t)(b * 8 + h) * KVLEN * 96);
;     const GAS unsigned char* Vg = (const GAS unsigned char*)(Vt + (size_t)(b * 8 + h) * 64 * KVLEN);
;     const unsigned ldsb = (unsigned)(size_t)lds;
;     const GAS unsigned char* src[3]; int stride[3]; unsigned dsto[3];
; #pragma unroll
;     for (int k = 0; k < 3; ++k) { int j = wave + 8 * k; if (j >= AT_NP) j -= 8; const int id = j * 64 + lane;
;         if (j < 13) { const int row = id / 13; int col = id - row * 13; if (col == 12) col = 0; src[k] = Kg + row * 192 + col * 16; stride[k] = 12288; }
;         else { const int idv = id - 832, d = idv / 9; int c = idv - d * 9; if (c == 8) c = 0; src[k] = Vg + ((size_t)d * KVLEN + c * 8) * 2; stride[k] = 128; }
;         dsto[k] = ldsb + j * 1024; }
	v_pk_mul_f32 v[26:27], v[28:29], v[44:45]
	v_lshlrev_b32_e32 v44, 16, v4
	v_cndmask_b32_e64 v27, v27, -v27, s[6:7]
	v_cndmask_b32_e64 v26, v26, -v26, s[6:7]
	v_pk_fma_f32 v[2:3], v[2:3], v[46:47], v[26:27]
	v_and_b32_e32 v45, 0xffff0000, v4
	v_cvt_pk_bf16_f32 v135, v2, v3
	s_waitcnt lgkmcnt(0)
	v_pk_mul_f32 v[2:3], v[28:29], v[32:33]
	global_load_dwordx4 v[26:29], v1, s[34:35] offset:48
	global_load_dwordx4 v[32:35], v1, s[34:35] offset:32
	v_pk_mul_f32 v[44:45], v[30:31], v[44:45] op_sel_hi:[0,1]
	ds_bpermute_b32 v48, v153, v44
	ds_bpermute_b32 v49, v153, v45
	v_cndmask_b32_e64 v3, v3, -v3, s[6:7]
	v_cndmask_b32_e64 v2, v2, -v2, s[6:7]
	v_pk_fma_f32 v[2:3], v[46:47], v[38:39], v[2:3]
	v_lshlrev_b32_e32 v46, 16, v40
	v_and_b32_e32 v47, 0xffff0000, v40
	s_waitcnt vmcnt(4)
	v_mov_b32_e32 v39, v12
	v_mov_b32_e32 v12, v11
	v_pk_mul_f32 v[46:47], v[42:43], v[46:47] op_sel_hi:[0,1]
	v_mov_b32_e32 v38, v10
	s_waitcnt lgkmcnt(0)
	v_pk_mul_f32 v[10:11], v[12:13], v[48:49]
	ds_bpermute_b32 v48, v153, v46
	ds_bpermute_b32 v49, v153, v47
	v_cndmask_b32_e64 v11, v11, -v11, s[6:7]
	v_cndmask_b32_e64 v10, v10, -v10, s[6:7]
	v_lshlrev_b32_e32 v4, 16, v5
	v_and_b32_e32 v5, 0xffff0000, v5
	v_pk_fma_f32 v[10:11], v[44:45], v[38:39], v[10:11]
	v_pk_mul_f32 v[4:5], v[30:31], v[4:5] op_sel_hi:[0,1]
	v_cvt_pk_bf16_f32 v136, v10, v11
	s_waitcnt lgkmcnt(0)
	v_pk_mul_f32 v[10:11], v[12:13], v[48:49]
	ds_bpermute_b32 v12, v153, v4
	ds_bpermute_b32 v13, v153, v5
	v_mov_b32_e32 v31, v8
	v_mov_b32_e32 v8, v7
	v_mov_b32_e32 v30, v6
	v_cndmask_b32_e64 v11, v11, -v11, s[6:7]
	s_waitcnt lgkmcnt(0)
	v_pk_mul_f32 v[6:7], v[8:9], v[12:13]
	v_lshlrev_b32_e32 v12, 16, v41
	v_and_b32_e32 v13, 0xffff0000, v41
	v_cndmask_b32_e64 v10, v10, -v10, s[6:7]
	v_pk_mul_f32 v[12:13], v[42:43], v[12:13] op_sel_hi:[0,1]
	v_pk_fma_f32 v[10:11], v[38:39], v[46:47], v[10:11]
	ds_bpermute_b32 v38, v153, v12
	ds_bpermute_b32 v39, v153, v13
	v_cvt_pk_bf16_f32 v139, v2, v3
	v_lshlrev_b32_e32 v2, 16, v14
	v_and_b32_e32 v3, 0xffff0000, v14
	v_cndmask_b32_e64 v7, v7, -v7, s[6:7]
	v_cndmask_b32_e64 v6, v6, -v6, s[6:7]
	v_pk_mul_f32 v[2:3], v[42:43], v[2:3] op_sel_hi:[0,1]
	v_pk_fma_f32 v[4:5], v[4:5], v[30:31], v[6:7]
	ds_bpermute_b32 v6, v153, v2
	ds_bpermute_b32 v7, v153, v3
	v_cvt_pk_bf16_f32 v137, v4, v5
	s_waitcnt lgkmcnt(2)
	v_pk_mul_f32 v[4:5], v[8:9], v[38:39]
	v_lshlrev_b32_e32 v8, 16, v15
	v_and_b32_e32 v9, 0xffff0000, v15
	v_cndmask_b32_e64 v5, v5, -v5, s[6:7]
	v_cndmask_b32_e64 v4, v4, -v4, s[6:7]
	v_pk_mul_f32 v[8:9], v[42:43], v[8:9] op_sel_hi:[0,1]
	v_pk_fma_f32 v[4:5], v[30:31], v[12:13], v[4:5]
	v_cvt_pk_bf16_f32 v140, v10, v11
	ds_bpermute_b32 v10, v153, v8
	ds_bpermute_b32 v11, v153, v9
	v_cvt_pk_bf16_f32 v141, v4, v5
	s_waitcnt vmcnt(2)
	v_mov_b32_e32 v5, v24
	v_mov_b32_e32 v24, v23
	s_waitcnt lgkmcnt(2)
	v_pk_mul_f32 v[6:7], v[24:25], v[6:7]
	v_mov_b32_e32 v4, v22
	v_cndmask_b32_e64 v7, v7, -v7, s[6:7]
	v_cndmask_b32_e64 v6, v6, -v6, s[6:7]
	v_pk_fma_f32 v[2:3], v[2:3], v[4:5], v[6:7]
	v_mov_b32_e32 v5, v20
	v_mov_b32_e32 v20, v19
	s_waitcnt lgkmcnt(0)
	v_pk_mul_f32 v[6:7], v[20:21], v[10:11]
	v_lshlrev_b32_e32 v10, 16, v16
	v_and_b32_e32 v11, 0xffff0000, v16
	v_pk_mul_f32 v[10:11], v[42:43], v[10:11] op_sel_hi:[0,1]
	ds_bpermute_b32 v12, v153, v10
	ds_bpermute_b32 v13, v153, v11
	v_mov_b32_e32 v4, v18
	v_cndmask_b32_e64 v7, v7, -v7, s[6:7]
	v_cndmask_b32_e64 v6, v6, -v6, s[6:7]
	v_pk_fma_f32 v[4:5], v[8:9], v[4:5], v[6:7]
	v_cvt_pk_bf16_f32 v142, v2, v3
	v_cvt_pk_bf16_f32 v143, v4, v5
	s_waitcnt vmcnt(0)
	v_mov_b32_e32 v7, v34
	v_mov_b32_e32 v34, v33
	s_waitcnt lgkmcnt(0)
	v_pk_mul_f32 v[8:9], v[34:35], v[12:13]
	v_lshlrev_b32_e32 v12, 16, v17
	v_and_b32_e32 v13, 0xffff0000, v17
	v_pk_mul_f32 v[12:13], v[42:43], v[12:13] op_sel_hi:[0,1]
	ds_bpermute_b32 v14, v153, v12
	ds_bpermute_b32 v15, v153, v13
	v_mov_b32_e32 v6, v32
	v_cndmask_b32_e64 v9, v9, -v9, s[6:7]
	v_cndmask_b32_e64 v8, v8, -v8, s[6:7]
	v_lshl_add_u64 v[4:5], s[24:25], 0, v[162:163]
	v_pk_fma_f32 v[6:7], v[10:11], v[6:7], v[8:9]
	v_mov_b32_e32 v9, v28
	v_mov_b32_e32 v28, v27
	v_lshl_add_u64 v[2:3], s[26:27], 0, v[160:161]
	v_lshl_add_u64 v[4:5], v[4:5], 0, v[164:165]
	s_waitcnt lgkmcnt(0)
; #define AT_ISSUE(t, slot) do { _Pragma("unroll") for (int k_ = 0; k_ < 3; ++k_) glds16(src[k_] + (size_t)(t) * stride[k_], (unsigned)__builtin_amdgcn_readfirstlane(dsto[k_] + (slot) * AT_SLOT)); } while (0)
; __device__ __forceinline__ void attn_unit(LAS unsigned char* lds, const GAS bf16_t* __restrict__ QR, const GAS float* __restrict__ ssq, const GAS float* __restrict__ RT, const GAS bf16_t* __restrict__ K, const GAS bf16_t* __restrict__ Vt, GAS bf16_t* __restrict__ A2, int b, int h, int qb, int tid, i ...
;     ...
;     for (int k = 0; k < 3; ++k) { int j = wave + 8 * k; if (j >= AT_NP) j -= 8; const int id = j * 64 + lane;
;         if (j < 13) { const int row = id / 13; int col = id - row * 13; if (col == 12) col = 0; src[k] = Kg + row * 192 + col * 16; stride[k] = 12288; }
;         else { const int idv = id - 832, d = idv / 9; int c = idv - d * 9; if (c == 8) c = 0; src[k] = Vg + ((size_t)d * KVLEN + c * 8) * 2; stride[k] = 128; }
;         dsto[k] = ldsb + j * 1024; }
;     ...
;     f32x16 oA0, oA1, oB0, oB1;
; #pragma unroll
;     for (int i = 0; i < 16; ++i) { oA0[i] = 0.f; oA1[i] = 0.f; oB0[i] = 0.f; oB1[i] = 0.f; }
;     float mA = -1e30f, mB = -1e30f, lA = 0.f, lB = 0.f;
;     constexpr int NT_ = KVLEN / 64;
;     AT_ISSUE(0, 0); AT_ISSUE(1, 1);
;     int slot = 0, nslot = 2;
	v_pk_mul_f32 v[10:11], v[28:29], v[14:15]
	v_cndmask_b32_e64 v3, v3, v5, s[12:13]
	v_cndmask_b32_e64 v2, v2, v4, s[12:13]
	v_lshl_add_u64 v[4:5], s[24:25], 0, v[168:169]
	v_mov_b32_e32 v8, v26
	v_cndmask_b32_e64 v11, v11, -v11, s[6:7]
	v_cndmask_b32_e64 v10, v10, -v10, s[6:7]
	v_cvt_pk_bf16_f32 v144, v6, v7
	v_lshl_add_u64 v[4:5], v[4:5], 0, v[170:171]
	v_lshl_add_u64 v[6:7], s[26:27], 0, v[166:167]
	v_pk_fma_f32 v[8:9], v[12:13], v[8:9], v[10:11]
	v_cndmask_b32_e64 v5, v7, v5, s[10:11]
	v_cndmask_b32_e64 v4, v6, v4, s[10:11]
	v_lshl_add_u64 v[6:7], s[24:25], 0, v[174:175]
	s_mov_b32 s1, m0
	s_mov_b32 m0, s60
	s_nop 0
	global_load_lds_dwordx4 v[2:3], off
	s_mov_b32 m0, s1
	v_cvt_pk_bf16_f32 v145, v8, v9
	v_lshl_add_u64 v[6:7], v[6:7], 0, v[176:177]
	v_lshl_add_u64 v[8:9], s[26:27], 0, v[172:173]
	s_mov_b32 s1, m0
	s_mov_b32 m0, s40
	s_nop 0
	global_load_lds_dwordx4 v[4:5], off
	s_mov_b32 m0, s1
	v_cndmask_b32_e64 v7, v9, v7, s[8:9]
	v_cndmask_b32_e64 v6, v8, v6, s[8:9]
	s_mov_b32 s1, m0
	s_mov_b32 m0, s41
	s_nop 0
	global_load_lds_dwordx4 v[6:7], off
	s_mov_b32 m0, s1
	v_lshl_add_u64 v[8:9], v[2:3], 0, s[92:93]
	s_add_i32 s1, s60, 0x5800
	s_mov_b32 s22, m0
	s_mov_b32 m0, s1
	s_nop 0
	global_load_lds_dwordx4 v[8:9], off
	s_mov_b32 m0, s22
	v_lshl_add_u64 v[8:9], v[4:5], 0, s[88:89]
	s_add_i32 s1, s40, 0x5800
	s_mov_b32 s22, m0
	s_mov_b32 m0, s1
	s_nop 0
	global_load_lds_dwordx4 v[8:9], off
	s_mov_b32 m0, s22
	v_lshl_add_u64 v[8:9], v[6:7], 0, s[90:91]
	v_mov_b32_e32 v14, v0
	v_mov_b32_e32 v15, v0
	v_cvt_pk_bf16_f32 v108, v60, v61
	v_cvt_pk_bf16_f32 v110, v62, v63
	v_cvt_pk_bf16_f32 v112, v64, v65
	v_cvt_pk_bf16_f32 v138, v36, v37
	s_add_i32 s1, s41, 0x5800
	s_mov_b32 s22, m0
	s_mov_b32 m0, s1
	s_nop 0
	global_load_lds_dwordx4 v[8:9], off
	s_mov_b32 m0, s22
	v_lshl_add_u64 v[180:181], v[6:7], 0, s[94:95]
	v_lshl_add_u64 v[182:183], v[4:5], 0, s[96:97]
	v_lshl_add_u64 v[184:185], v[2:3], 0, s[98:99]
	v_mov_b32_e32 v1, v0
	v_mov_b32_e32 v2, v0
	v_mov_b32_e32 v3, v0
	v_mov_b32_e32 v4, v0
	v_mov_b32_e32 v5, v0
	v_mov_b32_e32 v6, v0
	v_mov_b32_e32 v7, v0
	v_mov_b32_e32 v8, v0
	v_mov_b32_e32 v9, v0
	v_mov_b32_e32 v10, v0
	v_mov_b32_e32 v11, v0
	v_mov_b32_e32 v12, v0
	v_mov_b32_e32 v13, v0
	v_mov_b64_e32 v[64:65], v[14:15]
	v_mov_b64_e32 v[48:49], v[14:15]
	v_mov_b64_e32 v[32:33], v[14:15]
	v_mov_b64_e32 v[62:63], v[12:13]
	v_mov_b64_e32 v[60:61], v[10:11]
	v_mov_b64_e32 v[58:59], v[8:9]
	v_mov_b64_e32 v[56:57], v[6:7]
	v_mov_b64_e32 v[54:55], v[4:5]
	v_mov_b64_e32 v[52:53], v[2:3]
	v_mov_b64_e32 v[50:51], v[0:1]
	v_mov_b64_e32 v[46:47], v[12:13]
	v_mov_b64_e32 v[44:45], v[10:11]
	v_mov_b64_e32 v[42:43], v[8:9]
	v_mov_b64_e32 v[40:41], v[6:7]
	v_mov_b64_e32 v[38:39], v[4:5]
	v_mov_b64_e32 v[36:37], v[2:3]
	v_mov_b64_e32 v[34:35], v[0:1]
	v_mov_b64_e32 v[30:31], v[12:13]
	v_mov_b64_e32 v[28:29], v[10:11]
	v_mov_b64_e32 v[26:27], v[8:9]
	v_mov_b64_e32 v[24:25], v[6:7]
	v_mov_b64_e32 v[22:23], v[4:5]
	v_mov_b64_e32 v[20:21], v[2:3]
	v_mov_b64_e32 v[18:19], v[0:1]
	v_mov_b64_e32 v[16:17], v[14:15]
	v_mov_b64_e32 v[14:15], v[12:13]
	v_mov_b64_e32 v[12:13], v[10:11]
	v_mov_b64_e32 v[10:11], v[8:9]
	v_mov_b64_e32 v[8:9], v[6:7]
	v_mov_b64_e32 v[6:7], v[4:5]
	v_mov_b64_e32 v[4:5], v[2:3]
	v_mov_b64_e32 v[2:3], v[0:1]
	v_add_u32_e32 v1, v154, v207
	v_add_u32_e32 v204, v155, v154
	s_mov_b32 s1, 0
	v_mov_b32_e32 v188, 0
	v_mov_b32_e32 v189, 0
	v_mov_b32_e32 v190, 0
	v_mov_b32_e32 v191, 0
	v_mov_b32_e32 v192, 0
	v_mov_b32_e32 v193, 0
	v_mov_b32_e32 v194, 0
	v_mov_b32_e32 v195, 0
	v_mov_b32_e32 v196, 0
	v_mov_b32_e32 v197, 0
	v_mov_b32_e32 v198, 0
	v_mov_b32_e32 v199, 0
	v_mov_b32_e32 v200, 0
	v_mov_b32_e32 v201, 0
	v_mov_b32_e32 v202, 0
	v_mov_b32_e32 v203, 0
	v_mov_b32_e32 v234, 0
	v_mov_b32_e32 v235, 0
	v_mov_b32_e32 v236, 0
	v_mov_b32_e32 v237, 0
	v_mov_b32_e32 v238, 0
	v_mov_b32_e32 v239, 0
	v_mov_b32_e32 v240, 0
	v_mov_b32_e32 v241, 0
	v_mov_b32_e32 v242, 0
	v_mov_b32_e32 v243, 0
	v_mov_b32_e32 v244, 0
	v_mov_b32_e32 v245, 0
	v_mov_b32_e32 v246, 0
	v_mov_b32_e32 v247, 0
	v_mov_b32_e32 v248, 0
	v_mov_b32_e32 v249, 0
	s_mov_b32 s100, 0xff800000
	s_mov_b32 s101, 0xff800000
	s_branch .LBB0_135

; #define LAS __attribute__((address_space(3)))
; #define MFMA32(a, b, c) __builtin_amdgcn_mfma_f32_32x32x16_bf16((a), (b), (c), 0, 0, 0)
; #define AT_LMAX(P, MX) do { MX = fmaxf(fmaxf(P[0], P[1]), fmaxf(P[2], P[3])); \
;         _Pragma("unroll") for (int i_ = 4; i_ < 16; i_ += 4) MX = fmaxf(fmaxf(MX, P[i_]), fmaxf(fmaxf(P[i_ + 1], P[i_ + 2]), P[i_ + 3])); } while (0)
; __device__ __forceinline__ void attn_unit(LAS unsigned char* lds, const GAS bf16_t* __restrict__ QR, const GAS float* __restrict__ ssq, const GAS float* __restrict__ RT, const GAS bf16_t* __restrict__ K, const GAS bf16_t* __restrict__ Vt, GAS bf16_t* __restrict__ A2, int b, int h, int qb, int tid, i ...
;     ...
;             const LAS unsigned char* kb = sb + (32 * hh + r32s) * AT_KROW + hi * 16;
;             f32x16 pA, pB;
; #pragma unroll
;             for (int i = 0; i < 16; ++i) { pA[i] = 0.f; pB[i] = 0.f; }
; #pragma unroll
;             for (int d0 = 0; d0 < 6; ++d0) { const bf16x8 a0 = *(const LAS bf16x8*)(kb + d0 * 32); pA = MFMA32(a0, qa[d0], pA); pB = MFMA32(a0, qc[d0], pB); }
;             u32x4 pwA0, pwA1, pwB0, pwB1;
;             float mxA, mxB; AT_LMAX(pA, mxA); AT_LMAX(pB, mxB);
;             { const float oa = __shfl_xor(mxA, 32), ob = __shfl_xor(mxB, 32); mxA = fmaxf(mxA, oa); mxB = fmaxf(mxB, ob); }
;             AT_SOFTMAX(pA, mxA, mA, lA, oA0, oA1, pwA0, pwA1);
;             AT_SOFTMAX(pB, mxB, mB, lB, oB0, oB1, pwB0, pwB1);
.LBB0_139:
	s_mul_i32 s22, s1, 0x5800
	s_add_i32 s24, s22, 0
	v_add_u32_e32 v212, s24, v1
	ds_read_b128 v[66:69], v212
	ds_read_b128 v[214:217], v212 offset:32
	ds_read_b128 v[218:221], v212 offset:64
	ds_read_b128 v[222:225], v212 offset:96
	ds_read_b128 v[226:229], v212 offset:128
	ds_read_b128 v[230:233], v212 offset:160
	s_waitcnt lgkmcnt(5)
	v_mfma_f32_32x32x16_bf16 v[82:97], v[66:69], v[98:101], v[188:203]
	v_mfma_f32_32x32x16_bf16 v[66:81], v[66:69], v[118:121], v[234:249]
	s_waitcnt lgkmcnt(4)
	v_mfma_f32_32x32x16_bf16 v[82:97], v[214:217], v[102:105], v[82:97]
	v_mfma_f32_32x32x16_bf16 v[66:81], v[214:217], v[122:125], v[66:81]
	s_waitcnt lgkmcnt(3)
	v_mfma_f32_32x32x16_bf16 v[82:97], v[218:221], v[106:109], v[82:97]
	v_mfma_f32_32x32x16_bf16 v[66:81], v[218:221], v[126:129], v[66:81]
	s_waitcnt lgkmcnt(2)
	v_mfma_f32_32x32x16_bf16 v[82:97], v[222:225], v[110:113], v[82:97]
	v_mfma_f32_32x32x16_bf16 v[66:81], v[222:225], v[130:133], v[66:81]
	s_waitcnt lgkmcnt(1)
	v_mfma_f32_32x32x16_bf16 v[82:97], v[226:229], v[134:137], v[82:97]
	v_mfma_f32_32x32x16_bf16 v[66:81], v[226:229], v[138:141], v[66:81]
	s_waitcnt lgkmcnt(0)
	v_mfma_f32_32x32x16_bf16 v[82:97], v[230:233], v[114:117], v[82:97]
	v_mfma_f32_32x32x16_bf16 v[66:81], v[230:233], v[142:145], v[66:81]
	s_nop 10
	v_max_f32_e32 v210, v84, v85
	v_max3_f32 v210, v82, v83, v210
	v_max3_f32 v213, v87, v88, v89
	v_max3_f32 v214, v91, v92, v93
	v_max3_f32 v210, v210, v86, v213
	v_max3_f32 v215, v95, v96, v97
	v_max_f32_e32 v216, v68, v69
	v_max3_f32 v210, v210, v90, v214
	v_max3_f32 v216, v66, v67, v216
	v_max3_f32 v217, v71, v72, v73
	v_max3_f32 v214, v210, v94, v215
	v_max3_f32 v216, v216, v70, v217
	v_max3_f32 v217, v75, v76, v77
	ds_bpermute_b32 v215, v153, v214
	v_max3_f32 v210, v216, v74, v217
	v_max3_f32 v213, v79, v80, v81
	v_max3_f32 v210, v210, v78, v213
	ds_bpermute_b32 v213, v153, v210
	s_waitcnt lgkmcnt(1)
	v_max_f32_e32 v214, v214, v215
	v_cmp_lt_f32_e32 vcc, s100, v214
	s_cbranch_vccz .LBB0_141
	v_max_f32_e32 v215, s101, v214
	v_max_f32_e32 v214, 0, v215
	v_exp_f32_e64 v214, -v214
	v_sub_f32_e32 v188, v188, v215
	v_sub_f32_e32 v189, v189, v215
	v_sub_f32_e32 v190, v190, v215
	v_sub_f32_e32 v191, v191, v215
	v_sub_f32_e32 v192, v192, v215
	v_sub_f32_e32 v193, v193, v215
	v_sub_f32_e32 v194, v194, v215
	v_sub_f32_e32 v195, v195, v215
	v_sub_f32_e32 v196, v196, v215
	v_sub_f32_e32 v197, v197, v215
	v_sub_f32_e32 v198, v198, v215
	v_sub_f32_e32 v199, v199, v215
	v_sub_f32_e32 v200, v200, v215
	v_sub_f32_e32 v201, v201, v215
	v_sub_f32_e32 v202, v202, v215
	v_sub_f32_e32 v203, v203, v215
	v_sub_f32_e32 v82, v82, v215
	v_sub_f32_e32 v83, v83, v215
	v_sub_f32_e32 v84, v84, v215
	v_sub_f32_e32 v85, v85, v215
	v_sub_f32_e32 v86, v86, v215
	v_sub_f32_e32 v87, v87, v215
	v_sub_f32_e32 v88, v88, v215
	v_sub_f32_e32 v89, v89, v215
	v_sub_f32_e32 v90, v90, v215
	v_sub_f32_e32 v91, v91, v215
	v_sub_f32_e32 v92, v92, v215
	v_sub_f32_e32 v93, v93, v215
	v_sub_f32_e32 v94, v94, v215
	v_sub_f32_e32 v95, v95, v215
	v_sub_f32_e32 v96, v96, v215
	v_sub_f32_e32 v97, v97, v215
	v_pk_mul_f32 v[64:65], v[64:65], v[214:215] op_sel_hi:[1,0]
	v_pk_mul_f32 v[62:63], v[62:63], v[214:215] op_sel_hi:[1,0]
	v_pk_mul_f32 v[60:61], v[60:61], v[214:215] op_sel_hi:[1,0]
	v_pk_mul_f32 v[58:59], v[58:59], v[214:215] op_sel_hi:[1,0]
	v_pk_mul_f32 v[56:57], v[56:57], v[214:215] op_sel_hi:[1,0]
	v_pk_mul_f32 v[54:55], v[54:55], v[214:215] op_sel_hi:[1,0]
	v_pk_mul_f32 v[52:53], v[52:53], v[214:215] op_sel_hi:[1,0]
	v_pk_mul_f32 v[50:51], v[50:51], v[214:215] op_sel_hi:[1,0]
	v_pk_mul_f32 v[48:49], v[48:49], v[214:215] op_sel_hi:[1,0]
	v_pk_mul_f32 v[46:47], v[46:47], v[214:215] op_sel_hi:[1,0]
	v_pk_mul_f32 v[44:45], v[44:45], v[214:215] op_sel_hi:[1,0]
	v_pk_mul_f32 v[42:43], v[42:43], v[214:215] op_sel_hi:[1,0]
	v_pk_mul_f32 v[40:41], v[40:41], v[214:215] op_sel_hi:[1,0]
	v_pk_mul_f32 v[38:39], v[38:39], v[214:215] op_sel_hi:[1,0]
	v_pk_mul_f32 v[36:37], v[36:37], v[214:215] op_sel_hi:[1,0]
	v_pk_mul_f32 v[34:35], v[34:35], v[214:215] op_sel_hi:[1,0]
	v_mul_f32_e32 v211, v211, v214

; #define LAS __attribute__((address_space(3)))
; #define MFMA32(a, b, c) __builtin_amdgcn_mfma_f32_32x32x16_bf16((a), (b), (c), 0, 0, 0)
; #define AT_LMAX(P, MX) do { MX = fmaxf(fmaxf(P[0], P[1]), fmaxf(P[2], P[3])); \
;         _Pragma("unroll") for (int i_ = 4; i_ < 16; i_ += 4) MX = fmaxf(fmaxf(MX, P[i_]), fmaxf(fmaxf(P[i_ + 1], P[i_ + 2]), P[i_ + 3])); } while (0)
; __device__ __forceinline__ void attn_unit(LAS unsigned char* lds, const GAS bf16_t* __restrict__ QR, const GAS float* __restrict__ ssq, const GAS float* __restrict__ RT, const GAS bf16_t* __restrict__ K, const GAS bf16_t* __restrict__ Vt, GAS bf16_t* __restrict__ A2, int b, int h, int qb, int tid, i ...
;     ...
;             for (int d0 = 0; d0 < 6; ++d0) { const bf16x8 a0 = *(const LAS bf16x8*)(kb + d0 * 32); pA = MFMA32(a0, qa[d0], pA); pB = MFMA32(a0, qc[d0], pB); }
;             u32x4 pwA0, pwA1, pwB0, pwB1;
;             float mxA, mxB; AT_LMAX(pA, mxA); AT_LMAX(pB, mxB);
;             { const float oa = __shfl_xor(mxA, 32), ob = __shfl_xor(mxB, 32); mxA = fmaxf(mxA, oa); mxB = fmaxf(mxB, ob); }
;             AT_SOFTMAX(pA, mxA, mA, lA, oA0, oA1, pwA0, pwA1);
;             AT_SOFTMAX(pB, mxB, mB, lB, oB0, oB1, pwB0, pwB1);
;             const LAS unsigned char* vb = sb + AT_VOFF + r32 * AT_VROW + hi * 16 + hh * 64;
; #pragma unroll
;             for (int ks = 0; ks < 2; ++ks) {
;                 const bf16x8 va0 = *(const LAS bf16x8*)(vb + ks * 32), va1 = *(const LAS bf16x8*)(vb + 32 * AT_VROW + ks * 32);
;                 const bf16x8 pa = __builtin_bit_cast(bf16x8, ks ? pwA1 : pwA0), pb = __builtin_bit_cast(bf16x8, ks ? pwB1 : pwB0);
;                 oA0 = MFMA32(va0, pa, oA0); oA1 = MFMA32(va1, pa, oA1); oB0 = MFMA32(va0, pb, oB0); oB1 = MFMA32(va1, pb, oB1);
.LBB0_143:
	s_mov_b32 s100, 0x41000000
	s_mov_b32 s101, 0
	v_exp_f32_e32 v210, v82
	v_exp_f32_e32 v213, v83
	v_exp_f32_e32 v214, v84
	v_exp_f32_e32 v215, v85
	v_exp_f32_e32 v216, v86
	v_exp_f32_e32 v217, v87
	v_exp_f32_e32 v218, v88
	v_exp_f32_e32 v219, v89
	v_cvt_pk_bf16_f32 v86, v210, v213
	v_exp_f32_e32 v90, v90
	v_add_f32_e32 v210, v213, v210
	v_exp_f32_e32 v91, v91
	v_add_f32_e32 v210, v214, v210
	v_exp_f32_e32 v92, v92
	v_add_f32_e32 v210, v215, v210
	v_exp_f32_e32 v93, v93
	v_add_f32_e32 v210, v216, v210
	v_exp_f32_e32 v213, v66
	v_exp_f32_e32 v94, v94
	v_cvt_pk_bf16_f32 v87, v214, v215
	v_add_f32_e32 v210, v217, v210
	v_exp_f32_e32 v214, v67
	v_exp_f32_e32 v95, v95
	v_add_f32_e32 v210, v218, v210
	v_exp_f32_e32 v215, v68
	v_exp_f32_e32 v96, v96
	v_cvt_pk_bf16_f32 v88, v216, v217
	v_add_f32_e32 v210, v219, v210
	v_exp_f32_e32 v216, v69
	v_exp_f32_e32 v97, v97
	v_cvt_pk_bf16_f32 v82, v90, v91
	v_add_f32_e32 v90, v90, v210
	v_exp_f32_e32 v217, v70
	v_cvt_pk_bf16_f32 v89, v218, v219
	v_add_f32_e32 v90, v91, v90
	v_exp_f32_e32 v218, v71
	v_add_f32_e32 v90, v92, v90
	v_exp_f32_e32 v219, v72
	v_add_f32_e32 v90, v93, v90
	v_exp_f32_e32 v220, v73
	v_add_f32_e32 v90, v94, v90
	v_exp_f32_e32 v221, v74
	v_add_f32_e32 v90, v95, v90
	v_exp_f32_e32 v222, v75
	v_add_f32_e32 v90, v96, v90
	v_exp_f32_e32 v223, v76
	v_add_f32_e32 v90, v97, v90
	v_exp_f32_e32 v224, v77
	v_add_f32_e32 v211, v211, v90
	v_exp_f32_e32 v225, v78
	v_exp_f32_e32 v226, v79
	v_add_u32_e32 v210, s24, v204
	v_cvt_pk_bf16_f32 v83, v92, v93
	v_exp_f32_e32 v227, v80
	v_exp_f32_e32 v228, v81
	ds_read_b128 v[74:77], v210 offset:17920
	ds_read_b128 v[78:81], v210 offset:13312
	ds_read_b128 v[90:93], v210 offset:13344
	v_cvt_pk_bf16_f32 v70, v213, v214
	v_cvt_pk_bf16_f32 v71, v215, v216
	v_cvt_pk_bf16_f32 v72, v217, v218
	v_cvt_pk_bf16_f32 v73, v219, v220
	s_waitcnt lgkmcnt(1)
	v_mfma_f32_32x32x16_bf16 v[50:65], v[78:81], v[86:89], v[50:65]
	v_cvt_pk_bf16_f32 v84, v94, v95
	v_cvt_pk_bf16_f32 v85, v96, v97
	v_cvt_pk_bf16_f32 v66, v221, v222
	v_cvt_pk_bf16_f32 v67, v223, v224
	v_cvt_pk_bf16_f32 v68, v225, v226
	v_cvt_pk_bf16_f32 v69, v227, v228
	v_mfma_f32_32x32x16_bf16 v[18:33], v[78:81], v[70:73], v[18:33]
	v_mfma_f32_32x32x16_bf16 v[2:17], v[74:77], v[70:73], v[2:17]
	v_add_f32_e32 v213, v214, v213
	v_add_f32_e32 v213, v215, v213
	v_add_f32_e32 v213, v216, v213
	v_add_f32_e32 v213, v217, v213
	v_add_f32_e32 v213, v218, v213
	v_add_f32_e32 v213, v219, v213
	v_add_f32_e32 v213, v220, v213
	v_add_f32_e32 v213, v221, v213
	v_add_f32_e32 v213, v222, v213
	v_add_f32_e32 v213, v223, v213
	v_add_f32_e32 v213, v224, v213
	v_add_f32_e32 v213, v225, v213
	v_add_f32_e32 v213, v226, v213
	v_add_f32_e32 v213, v227, v213
	v_add_f32_e32 v213, v228, v213
	v_add_f32_e32 v209, v209, v213
	ds_read_b128 v[70:73], v210 offset:17952
	v_mfma_f32_32x32x16_bf16 v[34:49], v[74:77], v[86:89], v[34:49]
	s_waitcnt lgkmcnt(1)
	v_mfma_f32_32x32x16_bf16 v[50:65], v[90:93], v[82:85], v[50:65]
	s_waitcnt lgkmcnt(0)
	v_mfma_f32_32x32x16_bf16 v[34:49], v[70:73], v[82:85], v[34:49]
	ds_read_b128 v[82:85], v212 offset:6656
	ds_read_b128 v[230:233], v212 offset:6688
	ds_read_b128 v[214:217], v212 offset:6720
	ds_read_b128 v[218:221], v212 offset:6752
	ds_read_b128 v[222:225], v212 offset:6784
	ds_read_b128 v[226:229], v212 offset:6816
	v_mfma_f32_32x32x16_bf16 v[18:33], v[90:93], v[66:69], v[18:33]
	v_mfma_f32_32x32x16_bf16 v[2:17], v[70:73], v[66:69], v[2:17]
	s_waitcnt lgkmcnt(5)
	v_mfma_f32_32x32x16_bf16 v[66:81], v[82:85], v[98:101], v[188:203]
	s_waitcnt lgkmcnt(4)
	v_mfma_f32_32x32x16_bf16 v[66:81], v[230:233], v[102:105], v[66:81]
	s_waitcnt lgkmcnt(3)
	v_mfma_f32_32x32x16_bf16 v[66:81], v[214:217], v[106:109], v[66:81]
	s_waitcnt lgkmcnt(2)
	v_mfma_f32_32x32x16_bf16 v[66:81], v[218:221], v[110:113], v[66:81]
	s_waitcnt lgkmcnt(1)
	v_mfma_f32_32x32x16_bf16 v[66:81], v[222:225], v[134:137], v[66:81]
	s_waitcnt lgkmcnt(0)
	v_mfma_f32_32x32x16_bf16 v[66:81], v[226:229], v[114:117], v[66:81]
	s_nop 11
	v_max_f32_e32 v86, v68, v69
	v_max3_f32 v179, v66, v67, v86
	v_mfma_f32_32x32x16_bf16 v[82:97], v[82:85], v[118:121], v[234:249]
	v_max3_f32 v250, v71, v72, v73
	v_max3_f32 v251, v75, v76, v77
	v_max3_f32 v179, v179, v70, v250
	v_max3_f32 v252, v79, v80, v81
	v_max3_f32 v179, v179, v74, v251
	v_mfma_f32_32x32x16_bf16 v[82:97], v[230:233], v[122:125], v[82:97]
	v_mfma_f32_32x32x16_bf16 v[82:97], v[214:217], v[126:129], v[82:97]
	v_mfma_f32_32x32x16_bf16 v[82:97], v[218:221], v[130:133], v[82:97]
	v_mfma_f32_32x32x16_bf16 v[82:97], v[222:225], v[138:141], v[82:97]
	v_mfma_f32_32x32x16_bf16 v[82:97], v[226:229], v[142:145], v[82:97]
	s_nop 11
	v_max_f32_e32 v212, v84, v85
	v_max3_f32 v212, v82, v83, v212
	v_max3_f32 v230, v87, v88, v89
	v_max3_f32 v212, v212, v86, v230
	v_max3_f32 v230, v91, v92, v93
	v_max3_f32 v212, v212, v90, v230
	v_max3_f32 v230, v95, v96, v97
	v_max3_f32 v212, v212, v94, v230
	v_max3_f32 v230, v179, v78, v252
	ds_bpermute_b32 v231, v153, v230
	ds_bpermute_b32 v179, v153, v212
	s_waitcnt lgkmcnt(1)
	v_max_f32_e32 v230, v230, v231
	v_cmp_lt_f32_e32 vcc, s100, v230
	s_cbranch_vccz .LBB0_145
	v_max_f32_e32 v231, s101, v230
	v_max_f32_e32 v230, 0, v231
	v_exp_f32_e64 v230, -v230
	v_sub_f32_e32 v188, v188, v231
	v_sub_f32_e32 v189, v189, v231
	v_sub_f32_e32 v190, v190, v231
	v_sub_f32_e32 v191, v191, v231
	v_sub_f32_e32 v192, v192, v231
	v_sub_f32_e32 v193, v193, v231
	v_sub_f32_e32 v194, v194, v231
	v_sub_f32_e32 v195, v195, v231
	v_sub_f32_e32 v196, v196, v231
	v_sub_f32_e32 v197, v197, v231
	v_sub_f32_e32 v198, v198, v231
	v_sub_f32_e32 v199, v199, v231
	v_sub_f32_e32 v200, v200, v231
	v_sub_f32_e32 v201, v201, v231
	v_sub_f32_e32 v202, v202, v231
	v_sub_f32_e32 v203, v203, v231
	v_sub_f32_e32 v66, v66, v231
	v_sub_f32_e32 v67, v67, v231
	v_sub_f32_e32 v68, v68, v231
	v_sub_f32_e32 v69, v69, v231
	v_sub_f32_e32 v70, v70, v231
	v_sub_f32_e32 v71, v71, v231
	v_sub_f32_e32 v72, v72, v231
	v_sub_f32_e32 v73, v73, v231
	v_sub_f32_e32 v74, v74, v231
	v_sub_f32_e32 v75, v75, v231
	v_sub_f32_e32 v76, v76, v231
	v_sub_f32_e32 v77, v77, v231
	v_sub_f32_e32 v78, v78, v231
	v_sub_f32_e32 v79, v79, v231
	v_sub_f32_e32 v80, v80, v231
	v_sub_f32_e32 v81, v81, v231
	v_pk_mul_f32 v[64:65], v[64:65], v[230:231] op_sel_hi:[1,0]
	v_pk_mul_f32 v[62:63], v[62:63], v[230:231] op_sel_hi:[1,0]
	v_pk_mul_f32 v[60:61], v[60:61], v[230:231] op_sel_hi:[1,0]
	v_pk_mul_f32 v[58:59], v[58:59], v[230:231] op_sel_hi:[1,0]
	v_pk_mul_f32 v[56:57], v[56:57], v[230:231] op_sel_hi:[1,0]
	v_pk_mul_f32 v[54:55], v[54:55], v[230:231] op_sel_hi:[1,0]
	v_pk_mul_f32 v[52:53], v[52:53], v[230:231] op_sel_hi:[1,0]
	v_pk_mul_f32 v[50:51], v[50:51], v[230:231] op_sel_hi:[1,0]
	v_pk_mul_f32 v[48:49], v[48:49], v[230:231] op_sel_hi:[1,0]
	v_pk_mul_f32 v[46:47], v[46:47], v[230:231] op_sel_hi:[1,0]
	v_pk_mul_f32 v[44:45], v[44:45], v[230:231] op_sel_hi:[1,0]
	v_pk_mul_f32 v[42:43], v[42:43], v[230:231] op_sel_hi:[1,0]
	v_pk_mul_f32 v[40:41], v[40:41], v[230:231] op_sel_hi:[1,0]
	v_pk_mul_f32 v[38:39], v[38:39], v[230:231] op_sel_hi:[1,0]
	v_pk_mul_f32 v[36:37], v[36:37], v[230:231] op_sel_hi:[1,0]
	v_pk_mul_f32 v[34:35], v[34:35], v[230:231] op_sel_hi:[1,0]
	v_mul_f32_e32 v211, v211, v230

; __global__ void __launch_bounds__(512, 2) fwd_kernel(Args a) {
;     ...
;             const int upb = (NB * 8 * 16 + G - 1) / G, u0 = vcu * upb, u1 = min(NB * 8 * 16, u0 + upb);
;             __syncthreads();
;             for (int unit = u0; unit < u1; ++unit) { const int bh = unit >> 4, qb = unit & 15; attn_unit(lds, QR, ssq, RT, Kb, Vb, A2, bh >> 3, bh & 7, qb, tid, wave, lane); }
.LBB0_149:
	s_mov_b32 s100, 0
	v_mov_b32_e32 v188, 0x3c0881c4
	v_mov_b32_e32 v189, 0xbab64f3b
	v_mov_b32_e32 v190, 1
	v_mov_b32_e32 v191, 0xc00
	v_mov_b32_e32 v192, 0x42000
	v_mov_b32_e32 v193, 0x108000
	v_mov_b32_e32 v194, 0x1c00
	v_mov_b32_e32 v195, 0x1800
	v_mov_b32_e32 v196, 0x400
	v_mov_b32_e32 v197, 0x1400
	v_mov_b32_e32 v198, 0x800
	v_mov_b32_e32 v199, 0x1000
	v_mov_b32_e32 v200, 0xa200a00
	v_mov_b32_e32 v201, 0xa200800
	v_mov_b32_e32 v202, 0x7f800000
	v_mov_b32_e32 v203, 0x7fc00000
	v_mov_b32_e32 v204, 0xff800000
	s_mov_b32 s49, 0x8000
	s_mov_b32 s60, 0x2e8ba2e9
	s_movk_i32 s64, 0x5000
	s_movk_i32 s98, 0x2c00
	s_mov_b32 s99, 0x57fff
	s_movk_i32 s50, 0xf8
	s_movk_i32 s92, 0x1ff8
	s_movk_i32 s93, 0x4200
